# both residual GEMM epilogues (out-proj, MLP-down): f32 residual rows prefetched two rows ahead into dead fragment registers
# baseline (speedup 1.0000x reference)
; DEVI unsigned pk2(float lo, float hi) { unsigned r; asm("v_cvt_pk_bf16_f32 %0, %1, %2" : "=v"(r) : "v"(lo), "v"(hi)); return r; }
;   DEVI void operator()(const f32x4 (&acc)[2][2][4][2], const pg8::Unit& u, int wr, int wc, int fr, int fq) const {
;     ...
;       for (int m = 0; m < 4; ++m) {
;         const int row = u.pm * 256 + ai * 128 + wr * 64 + m * 16 + fr;
;         const bool use_snap = snap && (row & 2047) == 0;
;         float ss = 0.f;
; #pragma unroll
;         for (int bj = 0; bj < 2; ++bj) {
;           const int col = u.pn * 256 + bj * 128 + wc * 32 + fq * 8;
;           float* p = xf + (size_t)row * DM + col;
;           f32x4 x0 = *(const f32x4*)p, x1 = *(const f32x4*)(p + 4);
;           x0 += acc[ai][bj][m][0]; x1 += acc[ai][bj][m][1];
;           if (use_snap) { const float* sp = snap + (size_t)(row >> 11) * 1024 + col; x0 = *(const f32x4*)sp; x1 = *(const f32x4*)(sp + 4); }
;           *(f32x4*)p = x0; *(f32x4*)(p + 4) = x1;
;           u32x4 w; w.x = pk2(x0[0], x0[1]); w.y = pk2(x0[2], x0[3]); w.z = pk2(x1[0], x1[1]); w.w = pk2(x1[2], x1[3]);
;           *(u32x4*)(xb + (size_t)row * DM + col) = w;
;           ss += (x0[0] * x0[0] + x0[1] * x0[1] + x0[2] * x0[2] + x0[3] * x0[3]) + (x1[0] * x1[0] + x1[1] * x1[1] + x1[2] * x1[2] + x1[3] * x1[3]);
.LBB0_2207:
	s_lshl_b32 s11, s38, 8
	s_add_i32 s11, s11, s34
	v_or_b32_e32 v148, s11, v131
	v_bitop3_b32 v132, s11, v234, v131 bitop3:0xc8
	v_ashrrev_i32_e32 v149, 31, v148
	v_readlane_b32 s20, v252, 40
	v_lshl_or_b32 v146, s37, 8, v155
	v_cmp_eq_u32_e32 vcc, 0, v132
	v_lshlrev_b64 v[132:133], 12, v[148:149]
	v_readlane_b32 s21, v252, 41
	v_ashrrev_i32_e32 v147, 31, v146
	s_ashr_i32 s18, s11, 11
	v_lshl_add_u64 v[132:133], s[20:21], 0, v[132:133]
	v_lshl_add_u64 v[150:151], v[146:147], 2, v[132:133]
	v_mov_b32_e32 v162, 0x10000
	v_mov_b32_e32 v163, 0
	v_mov_b32_e32 v196, v150
	v_mov_b32_e32 v197, v151
	v_lshl_add_u64 v[198:199], v[196:197], 0, v[162:163]
	v_lshl_add_u64 v[200:201], v[198:199], 0, v[162:163]
	v_lshl_add_u64 v[202:203], v[200:201], 0, v[162:163]
	v_lshl_add_u64 v[204:205], v[162:163], 3, v[196:197]
	v_lshl_add_u64 v[206:207], v[204:205], 0, v[162:163]
	v_lshl_add_u64 v[208:209], v[206:207], 0, v[162:163]
	v_lshl_add_u64 v[210:211], v[208:209], 0, v[162:163]
	global_load_dwordx4 v[164:167], v[196:197], off offset:16
	global_load_dwordx4 v[168:171], v[196:197], off
	global_load_dwordx4 v[172:175], v[196:197], off offset:528
	global_load_dwordx4 v[176:179], v[196:197], off offset:512
	global_load_dwordx4 v[180:183], v[198:199], off offset:16
	global_load_dwordx4 v[184:187], v[198:199], off
	global_load_dwordx4 v[188:191], v[198:199], off offset:528
	global_load_dwordx4 v[192:195], v[198:199], off offset:512
	s_waitcnt vmcnt(4)
	v_mov_b32_e32 v132, v164
	v_mov_b32_e32 v133, v165
	v_mov_b32_e32 v134, v166
	v_mov_b32_e32 v135, v167
	v_mov_b32_e32 v158, v168
	v_mov_b32_e32 v159, v169
	v_mov_b32_e32 v160, v170
	v_mov_b32_e32 v161, v171
	s_ashr_i32 s19, s18, 31
	s_lshl_b64 s[18:19], s[18:19], 12
	v_readlane_b32 s22, v252, 42
	v_readlane_b32 s23, v252, 43
	v_pk_add_f32 v[124:125], v[124:125], v[134:135]
	v_pk_add_f32 v[128:129], v[128:129], v[160:161]
	v_pk_add_f32 v[126:127], v[126:127], v[158:159]
	v_pk_add_f32 v[122:123], v[122:123], v[132:133]
	s_and_saveexec_b64 s[20:21], vcc
	s_cbranch_execz .LBB0_2209
	s_add_u32 s22, s30, s18
	s_addc_u32 s23, s29, s19
	v_lshl_add_u64 v[126:127], v[146:147], 2, s[22:23]
	global_load_dwordx4 v[122:125], v[126:127], off offset:16
	s_nop 0
	global_load_dwordx4 v[126:129], v[126:127], off
.LBB0_2209:
	s_or_b64 exec, exec, s[20:21]
	v_readlane_b32 s20, v254, 6
	v_lshlrev_b64 v[152:153], 10, v[148:149]
	v_readlane_b32 s21, v254, 7
	s_waitcnt vmcnt(0)
	global_store_dwordx4 v[150:151], v[126:129], off
	global_store_dwordx4 v[150:151], v[122:125], off offset:16
	v_lshl_add_u64 v[152:153], v[152:153], 1, s[20:21]
	v_lshl_add_u64 v[152:153], v[146:147], 1, v[152:153]
	v_cvt_pk_bf16_f32 v132, v126, v127
	v_cvt_pk_bf16_f32 v133, v128, v129
	v_cvt_pk_bf16_f32 v134, v122, v123
	v_cvt_pk_bf16_f32 v135, v124, v125
	global_store_dwordx4 v[152:153], v[132:135], off
	s_nop 1
	v_mov_b32_e32 v132, v176
	v_mov_b32_e32 v133, v177
	v_mov_b32_e32 v134, v178
	v_mov_b32_e32 v135, v179
	v_mov_b32_e32 v158, v172
	v_mov_b32_e32 v159, v173
	v_mov_b32_e32 v160, v174
	v_mov_b32_e32 v161, v175
	global_load_dwordx4 v[164:167], v[200:201], off offset:16
	global_load_dwordx4 v[168:171], v[200:201], off
	global_load_dwordx4 v[172:175], v[200:201], off offset:528
	global_load_dwordx4 v[176:179], v[200:201], off offset:512
	v_pk_add_f32 v[120:121], v[120:121], v[134:135]
	v_pk_add_f32 v[118:119], v[118:119], v[132:133]
	v_pk_add_f32 v[116:117], v[116:117], v[160:161]
	v_pk_add_f32 v[114:115], v[114:115], v[158:159]
	s_and_saveexec_b64 s[20:21], vcc
	s_cbranch_execz .LBB0_2211
	s_add_u32 s18, s30, s18
	s_addc_u32 s19, s29, s19
	v_lshl_add_u64 v[118:119], v[146:147], 2, s[18:19]
	global_load_dwordx4 v[114:117], v[118:119], off offset:528
	s_nop 0
	global_load_dwordx4 v[118:121], v[118:119], off offset:512

; DEVI unsigned pk2(float lo, float hi) { unsigned r; asm("v_cvt_pk_bf16_f32 %0, %1, %2" : "=v"(r) : "v"(lo), "v"(hi)); return r; }
; template <int M> DEVI float shx(float v) { return __int_as_float(__builtin_amdgcn_ds_swizzle(__float_as_int(v), (M << 10) | 0x1f)); }
; DEVI float shx32(float v, int lane) { return __int_as_float(__builtin_amdgcn_ds_bpermute((lane ^ 32) << 2, __float_as_int(v))); }
;   DEVI void operator()(const f32x4 (&acc)[2][2][4][2], const pg8::Unit& u, int wr, int wc, int fr, int fq) const {
;     ...
;       for (int m = 0; m < 4; ++m) {
;         const int row = u.pm * 256 + ai * 128 + wr * 64 + m * 16 + fr;
;         const bool use_snap = snap && (row & 2047) == 0;
;         float ss = 0.f;
; #pragma unroll
;         for (int bj = 0; bj < 2; ++bj) {
;           const int col = u.pn * 256 + bj * 128 + wc * 32 + fq * 8;
;           float* p = xf + (size_t)row * DM + col;
;           f32x4 x0 = *(const f32x4*)p, x1 = *(const f32x4*)(p + 4);
;           x0 += acc[ai][bj][m][0]; x1 += acc[ai][bj][m][1];
;           if (use_snap) { const float* sp = snap + (size_t)(row >> 11) * 1024 + col; x0 = *(const f32x4*)sp; x1 = *(const f32x4*)(sp + 4); }
;           *(f32x4*)p = x0; *(f32x4*)(p + 4) = x1;
;           u32x4 w; w.x = pk2(x0[0], x0[1]); w.y = pk2(x0[2], x0[3]); w.z = pk2(x1[0], x1[1]); w.w = pk2(x1[2], x1[3]);
;           *(u32x4*)(xb + (size_t)row * DM + col) = w;
;           ss += (x0[0] * x0[0] + x0[1] * x0[1] + x0[2] * x0[2] + x0[3] * x0[3]) + (x1[0] * x1[0] + x1[1] * x1[1] + x1[2] * x1[2] + x1[3] * x1[3]);
;         }
;         ss += shx<16>(ss); ss += shx32(ss, fq * 16 + fr);
;         if (fq == 0) ssout[(size_t)row * 16 + u.pn * 4 + wc] = ss;
;       }
.LBB0_2213:
	s_or_b64 exec, exec, s[20:21]
	v_or_b32_e32 v114, 16, v148
	v_ashrrev_i32_e32 v115, 31, v114
	v_readlane_b32 s20, v252, 40
	v_lshlrev_b64 v[116:117], 12, v[114:115]
	v_readlane_b32 s21, v252, 41
	v_lshlrev_b64 v[126:127], 11, v[114:115]
	v_readlane_b32 s22, v252, 42
	v_lshl_add_u64 v[116:117], s[20:21], 0, v[116:117]
	v_lshl_add_u64 v[124:125], v[146:147], 2, v[116:117]
	s_waitcnt lgkmcnt(0)
	s_waitcnt vmcnt(11)
	v_mov_b32_e32 v116, v180
	v_mov_b32_e32 v117, v181
	v_mov_b32_e32 v118, v182
	v_mov_b32_e32 v119, v183
	v_mov_b32_e32 v120, v184
	v_mov_b32_e32 v121, v185
	v_mov_b32_e32 v122, v186
	v_mov_b32_e32 v123, v187
	v_readlane_b32 s20, v254, 6
	v_readlane_b32 s21, v254, 7
	v_readlane_b32 s23, v252, 43
	v_pk_add_f32 v[108:109], v[108:109], v[118:119]
	v_lshl_add_u64 v[126:127], s[20:21], 0, v[126:127]
	v_lshl_add_u64 v[126:127], v[146:147], 1, v[126:127]
	v_pk_add_f32 v[112:113], v[112:113], v[122:123]
	v_pk_add_f32 v[110:111], v[110:111], v[120:121]
	v_pk_add_f32 v[106:107], v[106:107], v[116:117]
	global_store_dwordx4 v[124:125], v[110:113], off
	global_store_dwordx4 v[124:125], v[106:109], off offset:16
	v_cvt_pk_bf16_f32 v116, v110, v111
	v_cvt_pk_bf16_f32 v117, v112, v113
	v_cvt_pk_bf16_f32 v118, v106, v107
	v_cvt_pk_bf16_f32 v119, v108, v109
	global_store_dwordx4 v[126:127], v[116:119], off
	s_nop 1
	v_mov_b32_e32 v116, v188
	v_mov_b32_e32 v117, v189
	v_mov_b32_e32 v118, v190
	v_mov_b32_e32 v119, v191
	v_mov_b32_e32 v120, v192
	v_mov_b32_e32 v121, v193
	v_mov_b32_e32 v122, v194
	v_mov_b32_e32 v123, v195
	global_load_dwordx4 v[180:183], v[202:203], off offset:16
	global_load_dwordx4 v[184:187], v[202:203], off
	global_load_dwordx4 v[188:191], v[202:203], off offset:528
	global_load_dwordx4 v[192:195], v[202:203], off offset:512
	v_mul_f32_e32 v111, v111, v111
	v_mul_f32_e32 v107, v107, v107
	v_fmac_f32_e32 v111, v110, v110
	v_fmac_f32_e32 v107, v106, v106
	v_fmac_f32_e32 v111, v112, v112
	v_fmac_f32_e32 v107, v108, v108
	v_fmac_f32_e32 v111, v113, v113
	v_fmac_f32_e32 v107, v109, v109
	v_add_f32_e32 v110, v107, v111
	v_pk_add_f32 v[106:107], v[98:99], v[116:117]
	v_pk_add_f32 v[98:99], v[102:103], v[120:121]
	v_mul_f32_e32 v103, v107, v107
	v_mul_f32_e32 v102, v99, v99
	v_pk_add_f32 v[108:109], v[100:101], v[118:119]
	v_pk_add_f32 v[100:101], v[104:105], v[122:123]
	v_fmac_f32_e32 v102, v98, v98
	v_fmac_f32_e32 v103, v106, v106
	v_fmac_f32_e32 v102, v100, v100
	v_fmac_f32_e32 v103, v108, v108
	v_fmac_f32_e32 v102, v101, v101
	v_fmac_f32_e32 v103, v109, v109
	v_add_f32_e32 v102, v103, v102
	v_add_f32_e32 v103, v110, v102
	ds_swizzle_b32 v104, v103 offset:swizzle(SWAP,16)
	global_store_dwordx4 v[124:125], v[98:101], off offset:512
	global_store_dwordx4 v[124:125], v[106:109], off offset:528
	v_cvt_pk_bf16_f32 v102, v98, v99
	v_cvt_pk_bf16_f32 v105, v108, v109
	s_waitcnt lgkmcnt(0)
	v_add_f32_e32 v98, v103, v104
	ds_bpermute_b32 v99, v156, v98
	v_cvt_pk_bf16_f32 v103, v100, v101
	v_cvt_pk_bf16_f32 v104, v106, v107
	global_store_dwordx4 v[126:127], v[102:105], off offset:256
	s_and_saveexec_b64 s[20:21], s[0:1]
	s_cbranch_execz .LBB0_2215
	v_lshlrev_b64 v[100:101], 6, v[114:115]
	v_lshl_add_u64 v[100:101], s[56:57], 0, v[100:101]
	v_lshl_add_u64 v[100:101], s[18:19], 2, v[100:101]
	s_lshl_b32 s22, s31, 2
	s_mov_b32 s23, s93
	v_lshl_add_u64 v[100:101], v[100:101], 0, s[22:23]
	s_waitcnt lgkmcnt(0)
	v_add_f32_e32 v98, v98, v99
	global_store_dword v[100:101], v98, off
.LBB0_2215:
	s_or_b64 exec, exec, s[20:21]
	v_or_b32_e32 v98, 32, v148
	s_waitcnt lgkmcnt(0)
	v_ashrrev_i32_e32 v99, 31, v98
	v_readlane_b32 s20, v252, 40
	v_lshlrev_b64 v[100:101], 12, v[98:99]
	v_readlane_b32 s21, v252, 41
	v_lshlrev_b64 v[110:111], 11, v[98:99]
	v_readlane_b32 s22, v252, 42
	v_lshl_add_u64 v[100:101], s[20:21], 0, v[100:101]
	v_lshl_add_u64 v[108:109], v[146:147], 2, v[100:101]
	s_waitcnt vmcnt(15)
	v_mov_b32_e32 v100, v164
	v_mov_b32_e32 v101, v165
	v_mov_b32_e32 v102, v166
	v_mov_b32_e32 v103, v167
	v_mov_b32_e32 v104, v168
	v_mov_b32_e32 v105, v169
	v_mov_b32_e32 v106, v170
	v_mov_b32_e32 v107, v171
	v_readlane_b32 s20, v254, 6
	v_readlane_b32 s21, v254, 7
	v_readlane_b32 s23, v252, 43
	v_pk_add_f32 v[92:93], v[92:93], v[102:103]
	v_lshl_add_u64 v[110:111], s[20:21], 0, v[110:111]
	v_lshl_add_u64 v[110:111], v[146:147], 1, v[110:111]
	v_pk_add_f32 v[96:97], v[96:97], v[106:107]
	v_pk_add_f32 v[94:95], v[94:95], v[104:105]
	v_pk_add_f32 v[90:91], v[90:91], v[100:101]
	global_store_dwordx4 v[108:109], v[94:97], off
	global_store_dwordx4 v[108:109], v[90:93], off offset:16
	v_cvt_pk_bf16_f32 v100, v94, v95
	v_cvt_pk_bf16_f32 v101, v96, v97
	v_cvt_pk_bf16_f32 v102, v90, v91
	v_cvt_pk_bf16_f32 v103, v92, v93
	global_store_dwordx4 v[110:111], v[100:103], off
	s_nop 1
	v_mov_b32_e32 v100, v172
	v_mov_b32_e32 v101, v173
	v_mov_b32_e32 v102, v174
	v_mov_b32_e32 v103, v175
	v_mov_b32_e32 v104, v176
	v_mov_b32_e32 v105, v177
	v_mov_b32_e32 v106, v178
	v_mov_b32_e32 v107, v179
	global_load_dwordx4 v[164:167], v[204:205], off offset:16
	global_load_dwordx4 v[168:171], v[204:205], off
	global_load_dwordx4 v[172:175], v[204:205], off offset:528
	global_load_dwordx4 v[176:179], v[204:205], off offset:512
	v_mul_f32_e32 v95, v95, v95
	v_mul_f32_e32 v91, v91, v91
	v_fmac_f32_e32 v95, v94, v94
	v_fmac_f32_e32 v91, v90, v90
	v_fmac_f32_e32 v95, v96, v96
	v_fmac_f32_e32 v91, v92, v92
	v_fmac_f32_e32 v95, v97, v97
	v_fmac_f32_e32 v91, v93, v93
	v_add_f32_e32 v94, v91, v95
	v_pk_add_f32 v[90:91], v[82:83], v[100:101]
	v_pk_add_f32 v[82:83], v[86:87], v[104:105]
	v_mul_f32_e32 v87, v91, v91
	v_mul_f32_e32 v86, v83, v83
	v_pk_add_f32 v[92:93], v[84:85], v[102:103]
	v_pk_add_f32 v[84:85], v[88:89], v[106:107]
	v_fmac_f32_e32 v86, v82, v82
	v_fmac_f32_e32 v87, v90, v90
	v_fmac_f32_e32 v86, v84, v84
	v_fmac_f32_e32 v87, v92, v92
	v_fmac_f32_e32 v86, v85, v85
	v_fmac_f32_e32 v87, v93, v93
	v_add_f32_e32 v86, v87, v86
	v_add_f32_e32 v87, v94, v86
	ds_swizzle_b32 v88, v87 offset:swizzle(SWAP,16)
	global_store_dwordx4 v[108:109], v[82:85], off offset:512
	global_store_dwordx4 v[108:109], v[90:93], off offset:528
	v_cvt_pk_bf16_f32 v86, v82, v83
	v_cvt_pk_bf16_f32 v89, v92, v93
	s_waitcnt lgkmcnt(0)
	v_add_f32_e32 v82, v87, v88
	ds_bpermute_b32 v83, v156, v82
	v_cvt_pk_bf16_f32 v87, v84, v85
	v_cvt_pk_bf16_f32 v88, v90, v91
	global_store_dwordx4 v[110:111], v[86:89], off offset:256
	s_and_saveexec_b64 s[20:21], s[0:1]
	s_cbranch_execz .LBB0_2217
	v_lshlrev_b64 v[84:85], 6, v[98:99]
	v_lshl_add_u64 v[84:85], s[56:57], 0, v[84:85]
	v_lshl_add_u64 v[84:85], s[18:19], 2, v[84:85]
	s_lshl_b32 s22, s31, 2
	s_mov_b32 s23, s93
	v_lshl_add_u64 v[84:85], v[84:85], 0, s[22:23]
	s_waitcnt lgkmcnt(0)
	v_add_f32_e32 v82, v82, v83
	global_store_dword v[84:85], v82, off
; DEVI unsigned pk2(float lo, float hi) { unsigned r; asm("v_cvt_pk_bf16_f32 %0, %1, %2" : "=v"(r) : "v"(lo), "v"(hi)); return r; }
; template <int M> DEVI float shx(float v) { return __int_as_float(__builtin_amdgcn_ds_swizzle(__float_as_int(v), (M << 10) | 0x1f)); }
; DEVI float shx32(float v, int lane) { return __int_as_float(__builtin_amdgcn_ds_bpermute((lane ^ 32) << 2, __float_as_int(v))); }
;   DEVI void operator()(const f32x4 (&acc)[2][2][4][2], const pg8::Unit& u, int wr, int wc, int fr, int fq) const {
;     ...
;       for (int m = 0; m < 4; ++m) {
;         const int row = u.pm * 256 + ai * 128 + wr * 64 + m * 16 + fr;
;         const bool use_snap = snap && (row & 2047) == 0;
;         float ss = 0.f;
; #pragma unroll
;         for (int bj = 0; bj < 2; ++bj) {
;           const int col = u.pn * 256 + bj * 128 + wc * 32 + fq * 8;
;           float* p = xf + (size_t)row * DM + col;
;           f32x4 x0 = *(const f32x4*)p, x1 = *(const f32x4*)(p + 4);
;           x0 += acc[ai][bj][m][0]; x1 += acc[ai][bj][m][1];
;           if (use_snap) { const float* sp = snap + (size_t)(row >> 11) * 1024 + col; x0 = *(const f32x4*)sp; x1 = *(const f32x4*)(sp + 4); }
;           *(f32x4*)p = x0; *(f32x4*)(p + 4) = x1;
;           u32x4 w; w.x = pk2(x0[0], x0[1]); w.y = pk2(x0[2], x0[3]); w.z = pk2(x1[0], x1[1]); w.w = pk2(x1[2], x1[3]);
;           *(u32x4*)(xb + (size_t)row * DM + col) = w;
;           ss += (x0[0] * x0[0] + x0[1] * x0[1] + x0[2] * x0[2] + x0[3] * x0[3]) + (x1[0] * x1[0] + x1[1] * x1[1] + x1[2] * x1[2] + x1[3] * x1[3]);
;         }
;         ss += shx<16>(ss); ss += shx32(ss, fq * 16 + fr);
;         if (fq == 0) ssout[(size_t)row * 16 + u.pn * 4 + wc] = ss;
;       }
.LBB0_2217:
	s_or_b64 exec, exec, s[20:21]
	v_or_b32_e32 v82, 48, v148
	s_waitcnt lgkmcnt(0)
	v_ashrrev_i32_e32 v83, 31, v82
	v_readlane_b32 s20, v252, 40
	v_lshlrev_b64 v[84:85], 12, v[82:83]
	v_readlane_b32 s21, v252, 41
	v_lshlrev_b64 v[94:95], 11, v[82:83]
	v_readlane_b32 s22, v252, 42
	v_lshl_add_u64 v[84:85], s[20:21], 0, v[84:85]
	v_lshl_add_u64 v[92:93], v[146:147], 2, v[84:85]
	s_waitcnt vmcnt(15)
	v_mov_b32_e32 v84, v180
	v_mov_b32_e32 v85, v181
	v_mov_b32_e32 v86, v182
	v_mov_b32_e32 v87, v183
	v_mov_b32_e32 v88, v184
	v_mov_b32_e32 v89, v185
	v_mov_b32_e32 v90, v186
	v_mov_b32_e32 v91, v187
	v_readlane_b32 s20, v254, 6
	v_readlane_b32 s21, v254, 7
	v_readlane_b32 s23, v252, 43
	v_pk_add_f32 v[76:77], v[76:77], v[86:87]
	v_lshl_add_u64 v[94:95], s[20:21], 0, v[94:95]
	v_lshl_add_u64 v[94:95], v[146:147], 1, v[94:95]
	v_pk_add_f32 v[80:81], v[80:81], v[90:91]
	v_pk_add_f32 v[78:79], v[78:79], v[88:89]
	v_pk_add_f32 v[74:75], v[74:75], v[84:85]
	global_store_dwordx4 v[92:93], v[78:81], off
	global_store_dwordx4 v[92:93], v[74:77], off offset:16
	v_cvt_pk_bf16_f32 v84, v78, v79
	v_cvt_pk_bf16_f32 v85, v80, v81
	v_cvt_pk_bf16_f32 v86, v74, v75
	v_cvt_pk_bf16_f32 v87, v76, v77
	global_store_dwordx4 v[94:95], v[84:87], off
	s_nop 1
	v_mov_b32_e32 v84, v188
	v_mov_b32_e32 v85, v189
	v_mov_b32_e32 v86, v190
	v_mov_b32_e32 v87, v191
	v_mov_b32_e32 v88, v192
	v_mov_b32_e32 v89, v193
	v_mov_b32_e32 v90, v194
	v_mov_b32_e32 v91, v195
	global_load_dwordx4 v[180:183], v[206:207], off offset:16
	global_load_dwordx4 v[184:187], v[206:207], off
	global_load_dwordx4 v[188:191], v[206:207], off offset:528
	global_load_dwordx4 v[192:195], v[206:207], off offset:512
	v_mul_f32_e32 v79, v79, v79
	v_mul_f32_e32 v75, v75, v75
	v_fmac_f32_e32 v79, v78, v78
	v_fmac_f32_e32 v75, v74, v74
	v_fmac_f32_e32 v79, v80, v80
	v_fmac_f32_e32 v75, v76, v76
	v_fmac_f32_e32 v79, v81, v81
	v_fmac_f32_e32 v75, v77, v77
	v_add_f32_e32 v78, v75, v79
	v_pk_add_f32 v[74:75], v[66:67], v[84:85]
	v_pk_add_f32 v[66:67], v[70:71], v[88:89]
	v_mul_f32_e32 v71, v75, v75
	v_mul_f32_e32 v70, v67, v67
	v_pk_add_f32 v[76:77], v[68:69], v[86:87]
	v_pk_add_f32 v[68:69], v[72:73], v[90:91]
	v_fmac_f32_e32 v70, v66, v66
	v_fmac_f32_e32 v71, v74, v74
	v_fmac_f32_e32 v70, v68, v68
	v_fmac_f32_e32 v71, v76, v76
	v_fmac_f32_e32 v70, v69, v69
	v_fmac_f32_e32 v71, v77, v77
	v_add_f32_e32 v70, v71, v70
	v_add_f32_e32 v71, v78, v70
	ds_swizzle_b32 v72, v71 offset:swizzle(SWAP,16)
	global_store_dwordx4 v[92:93], v[66:69], off offset:512
	global_store_dwordx4 v[92:93], v[74:77], off offset:528
	v_cvt_pk_bf16_f32 v70, v66, v67
	v_cvt_pk_bf16_f32 v73, v76, v77
	s_waitcnt lgkmcnt(0)
	v_add_f32_e32 v66, v71, v72
	ds_bpermute_b32 v67, v156, v66
	v_cvt_pk_bf16_f32 v71, v68, v69
	v_cvt_pk_bf16_f32 v72, v74, v75
	global_store_dwordx4 v[94:95], v[70:73], off offset:256
	s_and_saveexec_b64 s[20:21], s[0:1]
	s_cbranch_execz .LBB0_2219
	v_lshlrev_b64 v[68:69], 6, v[82:83]
	v_lshl_add_u64 v[68:69], s[56:57], 0, v[68:69]
	v_lshl_add_u64 v[68:69], s[18:19], 2, v[68:69]
	s_lshl_b32 s22, s31, 2
	s_mov_b32 s23, s93
	v_lshl_add_u64 v[68:69], v[68:69], 0, s[22:23]
	s_waitcnt lgkmcnt(0)
	v_add_f32_e32 v66, v66, v67
	global_store_dword v[68:69], v66, off
.LBB0_2219:
	s_or_b64 exec, exec, s[20:21]
	s_addk_i32 s11, 0x80
	v_or_b32_e32 v66, s11, v131
	s_waitcnt lgkmcnt(0)
	v_bitop3_b32 v67, s11, v234, v131 bitop3:0xc8
	v_cmp_eq_u32_e32 vcc, 0, v67
	v_ashrrev_i32_e32 v67, 31, v66
	v_readlane_b32 s40, v252, 40
	v_lshlrev_b64 v[68:69], 12, v[66:67]
	v_readlane_b32 s41, v252, 41
	s_ashr_i32 s20, s11, 11
	s_ashr_i32 s21, s20, 31
	v_lshl_add_u64 v[68:69], s[40:41], 0, v[68:69]
	v_lshl_add_u64 v[68:69], v[146:147], 2, v[68:69]
	s_waitcnt vmcnt(15)
	v_mov_b32_e32 v70, v164
	v_mov_b32_e32 v71, v165
	v_mov_b32_e32 v72, v166
	v_mov_b32_e32 v73, v167
	v_mov_b32_e32 v74, v168
	v_mov_b32_e32 v75, v169
	v_mov_b32_e32 v76, v170
	v_mov_b32_e32 v77, v171
	s_lshl_b64 s[20:21], s[20:21], 12
	v_readlane_b32 s42, v252, 42
	v_readlane_b32 s43, v252, 43
	v_pk_add_f32 v[60:61], v[60:61], v[72:73]
	v_pk_add_f32 v[64:65], v[64:65], v[76:77]
	v_pk_add_f32 v[62:63], v[62:63], v[74:75]
	v_pk_add_f32 v[58:59], v[58:59], v[70:71]
	s_and_saveexec_b64 s[22:23], vcc
	s_cbranch_execz .LBB0_2221
	s_add_u32 s38, s30, s20
	s_addc_u32 s39, s29, s21
	v_lshl_add_u64 v[62:63], v[146:147], 2, s[38:39]
	global_load_dwordx4 v[58:61], v[62:63], off offset:16
	s_nop 0
	global_load_dwordx4 v[62:65], v[62:63], off
.LBB0_2221:
	s_or_b64 exec, exec, s[22:23]
	v_readlane_b32 s22, v254, 6
	v_lshlrev_b64 v[70:71], 10, v[66:67]
	v_readlane_b32 s23, v254, 7
	s_waitcnt vmcnt(0)
	global_store_dwordx4 v[68:69], v[62:65], off
	global_store_dwordx4 v[68:69], v[58:61], off offset:16
	v_lshl_add_u64 v[70:71], v[70:71], 1, s[22:23]
	v_lshl_add_u64 v[70:71], v[146:147], 1, v[70:71]
	v_cvt_pk_bf16_f32 v72, v62, v63
	v_cvt_pk_bf16_f32 v73, v64, v65
	v_cvt_pk_bf16_f32 v74, v58, v59
	v_cvt_pk_bf16_f32 v75, v60, v61
	global_store_dwordx4 v[70:71], v[72:75], off
	s_nop 1
	v_mov_b32_e32 v72, v176
	v_mov_b32_e32 v73, v177
	v_mov_b32_e32 v74, v178
	v_mov_b32_e32 v75, v179
	v_mov_b32_e32 v76, v172
	v_mov_b32_e32 v77, v173
	v_mov_b32_e32 v78, v174
	v_mov_b32_e32 v79, v175
	global_load_dwordx4 v[164:167], v[208:209], off offset:16
	global_load_dwordx4 v[168:171], v[208:209], off
	global_load_dwordx4 v[172:175], v[208:209], off offset:528
	global_load_dwordx4 v[176:179], v[208:209], off offset:512
	v_pk_add_f32 v[56:57], v[56:57], v[74:75]
	v_pk_add_f32 v[54:55], v[54:55], v[72:73]
	v_pk_add_f32 v[52:53], v[52:53], v[78:79]
	v_pk_add_f32 v[50:51], v[50:51], v[76:77]
	s_and_saveexec_b64 s[22:23], vcc
	s_cbranch_execz .LBB0_2223
	s_add_u32 s20, s30, s20
	s_addc_u32 s21, s29, s21
	v_lshl_add_u64 v[54:55], v[146:147], 2, s[20:21]
	global_load_dwordx4 v[50:53], v[54:55], off offset:528
	s_nop 0
	global_load_dwordx4 v[54:57], v[54:55], off offset:512

; DEVI unsigned pk2(float lo, float hi) { unsigned r; asm("v_cvt_pk_bf16_f32 %0, %1, %2" : "=v"(r) : "v"(lo), "v"(hi)); return r; }
; template <int M> DEVI float shx(float v) { return __int_as_float(__builtin_amdgcn_ds_swizzle(__float_as_int(v), (M << 10) | 0x1f)); }
; DEVI float shx32(float v, int lane) { return __int_as_float(__builtin_amdgcn_ds_bpermute((lane ^ 32) << 2, __float_as_int(v))); }
;   DEVI void operator()(const f32x4 (&acc)[2][2][4][2], const pg8::Unit& u, int wr, int wc, int fr, int fq) const {
;     ...
;       for (int m = 0; m < 4; ++m) {
;         const int row = u.pm * 256 + ai * 128 + wr * 64 + m * 16 + fr;
;         const bool use_snap = snap && (row & 2047) == 0;
;         float ss = 0.f;
; #pragma unroll
;         for (int bj = 0; bj < 2; ++bj) {
;           const int col = u.pn * 256 + bj * 128 + wc * 32 + fq * 8;
;           float* p = xf + (size_t)row * DM + col;
;           f32x4 x0 = *(const f32x4*)p, x1 = *(const f32x4*)(p + 4);
;           x0 += acc[ai][bj][m][0]; x1 += acc[ai][bj][m][1];
;           if (use_snap) { const float* sp = snap + (size_t)(row >> 11) * 1024 + col; x0 = *(const f32x4*)sp; x1 = *(const f32x4*)(sp + 4); }
;           *(f32x4*)p = x0; *(f32x4*)(p + 4) = x1;
;           u32x4 w; w.x = pk2(x0[0], x0[1]); w.y = pk2(x0[2], x0[3]); w.z = pk2(x1[0], x1[1]); w.w = pk2(x1[2], x1[3]);
;           *(u32x4*)(xb + (size_t)row * DM + col) = w;
;           ss += (x0[0] * x0[0] + x0[1] * x0[1] + x0[2] * x0[2] + x0[3] * x0[3]) + (x1[0] * x1[0] + x1[1] * x1[1] + x1[2] * x1[2] + x1[3] * x1[3]);
;         }
;         ss += shx<16>(ss); ss += shx32(ss, fq * 16 + fr);
;         if (fq == 0) ssout[(size_t)row * 16 + u.pn * 4 + wc] = ss;
;       }
.LBB0_2225:
	s_or_b64 exec, exec, s[20:21]
	v_or_b32_e32 v50, 16, v66
	v_ashrrev_i32_e32 v51, 31, v50
	v_readlane_b32 s20, v252, 40
	v_lshlrev_b64 v[52:53], 12, v[50:51]
	v_readlane_b32 s21, v252, 41
	v_readlane_b32 s22, v252, 42
	v_readlane_b32 s23, v252, 43
	v_lshl_add_u64 v[52:53], s[20:21], 0, v[52:53]
	v_lshl_add_u64 v[60:61], v[146:147], 2, v[52:53]
	s_waitcnt lgkmcnt(0)
	s_waitcnt vmcnt(15)
	v_mov_b32_e32 v52, v180
	v_mov_b32_e32 v53, v181
	v_mov_b32_e32 v54, v182
	v_mov_b32_e32 v55, v183
	v_mov_b32_e32 v56, v184
	v_mov_b32_e32 v57, v185
	v_mov_b32_e32 v58, v186
	v_mov_b32_e32 v59, v187
	v_readlane_b32 s20, v254, 6
	v_readlane_b32 s21, v254, 7
	v_pk_add_f32 v[42:43], v[42:43], v[52:53]
	v_pk_add_f32 v[48:49], v[48:49], v[58:59]
	v_pk_add_f32 v[46:47], v[46:47], v[56:57]
	v_pk_add_f32 v[44:45], v[44:45], v[54:55]
	global_store_dwordx4 v[60:61], v[46:49], off
	global_store_dwordx4 v[60:61], v[42:45], off offset:16
	v_cvt_pk_bf16_f32 v52, v46, v47
	v_cvt_pk_bf16_f32 v54, v42, v43
	v_lshlrev_b64 v[56:57], 11, v[50:51]
	v_mul_f32_e32 v47, v47, v47
	v_mul_f32_e32 v43, v43, v43
	v_lshl_add_u64 v[56:57], s[20:21], 0, v[56:57]
	v_fmac_f32_e32 v47, v46, v46
	v_fmac_f32_e32 v43, v42, v42
	v_lshl_add_u64 v[56:57], v[146:147], 1, v[56:57]
	v_fmac_f32_e32 v47, v48, v48
	v_fmac_f32_e32 v43, v44, v44
	v_cvt_pk_bf16_f32 v53, v48, v49
	v_cvt_pk_bf16_f32 v55, v44, v45
	global_store_dwordx4 v[56:57], v[52:55], off
	v_fmac_f32_e32 v47, v49, v49
	v_fmac_f32_e32 v43, v45, v45
	v_add_f32_e32 v52, v47, v43
	s_nop 1
	v_mov_b32_e32 v42, v188
	v_mov_b32_e32 v43, v189
	v_mov_b32_e32 v44, v190
	v_mov_b32_e32 v45, v191
	v_mov_b32_e32 v46, v192
	v_mov_b32_e32 v47, v193
	v_mov_b32_e32 v48, v194
	v_mov_b32_e32 v49, v195
	global_load_dwordx4 v[180:183], v[210:211], off offset:16
	global_load_dwordx4 v[184:187], v[210:211], off
	global_load_dwordx4 v[188:191], v[210:211], off offset:528
	global_load_dwordx4 v[192:195], v[210:211], off offset:512
	v_pk_add_f32 v[34:35], v[34:35], v[42:43]
	v_pk_add_f32 v[40:41], v[40:41], v[48:49]
	v_pk_add_f32 v[38:39], v[38:39], v[46:47]
	v_pk_add_f32 v[36:37], v[36:37], v[44:45]
	global_store_dwordx4 v[60:61], v[38:41], off offset:512
	global_store_dwordx4 v[60:61], v[34:37], off offset:528
	v_cvt_pk_bf16_f32 v42, v38, v39
	v_cvt_pk_bf16_f32 v44, v34, v35
	v_cvt_pk_bf16_f32 v43, v40, v41
	v_cvt_pk_bf16_f32 v45, v36, v37
	s_nop 0
	v_mul_f32_e32 v39, v39, v39
	v_mul_f32_e32 v35, v35, v35
	v_fmac_f32_e32 v39, v38, v38
	v_fmac_f32_e32 v35, v34, v34
	v_fmac_f32_e32 v39, v40, v40
	v_fmac_f32_e32 v35, v36, v36
	v_fmac_f32_e32 v39, v41, v41
	v_fmac_f32_e32 v35, v37, v37
	v_add_f32_e32 v34, v39, v35
	v_add_f32_e32 v34, v52, v34
	ds_swizzle_b32 v35, v34 offset:swizzle(SWAP,16)
	global_store_dwordx4 v[56:57], v[42:45], off offset:256
	s_waitcnt lgkmcnt(0)
	v_add_f32_e32 v34, v34, v35
	ds_bpermute_b32 v35, v156, v34
	s_and_saveexec_b64 s[20:21], s[0:1]
	s_cbranch_execz .LBB0_2227
	v_lshlrev_b64 v[36:37], 6, v[50:51]
	v_lshl_add_u64 v[36:37], s[56:57], 0, v[36:37]
	v_lshl_add_u64 v[36:37], s[18:19], 2, v[36:37]
	s_lshl_b32 s22, s31, 2
	s_mov_b32 s23, s93
	v_lshl_add_u64 v[36:37], v[36:37], 0, s[22:23]
	s_waitcnt lgkmcnt(0)
	v_add_f32_e32 v34, v34, v35
	global_store_dword v[36:37], v34, off
; DEVI unsigned pk2(float lo, float hi) { unsigned r; asm("v_cvt_pk_bf16_f32 %0, %1, %2" : "=v"(r) : "v"(lo), "v"(hi)); return r; }
; template <int M> DEVI float shx(float v) { return __int_as_float(__builtin_amdgcn_ds_swizzle(__float_as_int(v), (M << 10) | 0x1f)); }
; DEVI float shx32(float v, int lane) { return __int_as_float(__builtin_amdgcn_ds_bpermute((lane ^ 32) << 2, __float_as_int(v))); }
;   DEVI void operator()(const f32x4 (&acc)[2][2][4][2], const pg8::Unit& u, int wr, int wc, int fr, int fq) const {
;     ...
;       for (int m = 0; m < 4; ++m) {
;         const int row = u.pm * 256 + ai * 128 + wr * 64 + m * 16 + fr;
;         const bool use_snap = snap && (row & 2047) == 0;
;         float ss = 0.f;
; #pragma unroll
;         for (int bj = 0; bj < 2; ++bj) {
;           const int col = u.pn * 256 + bj * 128 + wc * 32 + fq * 8;
;           float* p = xf + (size_t)row * DM + col;
;           f32x4 x0 = *(const f32x4*)p, x1 = *(const f32x4*)(p + 4);
;           x0 += acc[ai][bj][m][0]; x1 += acc[ai][bj][m][1];
;           if (use_snap) { const float* sp = snap + (size_t)(row >> 11) * 1024 + col; x0 = *(const f32x4*)sp; x1 = *(const f32x4*)(sp + 4); }
;           *(f32x4*)p = x0; *(f32x4*)(p + 4) = x1;
;           u32x4 w; w.x = pk2(x0[0], x0[1]); w.y = pk2(x0[2], x0[3]); w.z = pk2(x1[0], x1[1]); w.w = pk2(x1[2], x1[3]);
;           *(u32x4*)(xb + (size_t)row * DM + col) = w;
;           ss += (x0[0] * x0[0] + x0[1] * x0[1] + x0[2] * x0[2] + x0[3] * x0[3]) + (x1[0] * x1[0] + x1[1] * x1[1] + x1[2] * x1[2] + x1[3] * x1[3]);
;         }
;         ss += shx<16>(ss); ss += shx32(ss, fq * 16 + fr);
;         if (fq == 0) ssout[(size_t)row * 16 + u.pn * 4 + wc] = ss;
;       }
.LBB0_2227:
	s_or_b64 exec, exec, s[20:21]
	v_or_b32_e32 v34, 32, v66
	s_waitcnt lgkmcnt(0)
	v_ashrrev_i32_e32 v35, 31, v34
	v_readlane_b32 s20, v252, 40
	v_lshlrev_b64 v[36:37], 12, v[34:35]
	v_readlane_b32 s21, v252, 41
	v_readlane_b32 s22, v252, 42
	v_readlane_b32 s23, v252, 43
	v_lshl_add_u64 v[36:37], s[20:21], 0, v[36:37]
	v_lshl_add_u64 v[44:45], v[146:147], 2, v[36:37]
	s_waitcnt vmcnt(15)
	v_mov_b32_e32 v36, v164
	v_mov_b32_e32 v37, v165
	v_mov_b32_e32 v38, v166
	v_mov_b32_e32 v39, v167
	v_mov_b32_e32 v40, v168
	v_mov_b32_e32 v41, v169
	v_mov_b32_e32 v42, v170
	v_mov_b32_e32 v43, v171
	v_readlane_b32 s20, v254, 6
	v_readlane_b32 s21, v254, 7
	v_pk_add_f32 v[24:25], v[24:25], v[36:37]
	v_pk_add_f32 v[30:31], v[30:31], v[42:43]
	v_pk_add_f32 v[28:29], v[28:29], v[40:41]
	v_pk_add_f32 v[26:27], v[26:27], v[38:39]
	global_store_dwordx4 v[44:45], v[28:31], off
	global_store_dwordx4 v[44:45], v[24:27], off offset:16
	v_cvt_pk_bf16_f32 v36, v28, v29
	v_cvt_pk_bf16_f32 v38, v24, v25
	v_lshlrev_b64 v[40:41], 11, v[34:35]
	v_mul_f32_e32 v29, v29, v29
	v_mul_f32_e32 v25, v25, v25
	v_lshl_add_u64 v[40:41], s[20:21], 0, v[40:41]
	v_fmac_f32_e32 v29, v28, v28
	v_fmac_f32_e32 v25, v24, v24
	v_lshl_add_u64 v[40:41], v[146:147], 1, v[40:41]
	v_fmac_f32_e32 v29, v30, v30
	v_fmac_f32_e32 v25, v26, v26
	v_cvt_pk_bf16_f32 v37, v30, v31
	v_cvt_pk_bf16_f32 v39, v26, v27
	global_store_dwordx4 v[40:41], v[36:39], off
	v_fmac_f32_e32 v29, v31, v31
	v_fmac_f32_e32 v25, v27, v27
	v_add_f32_e32 v36, v29, v25
	s_nop 1
	v_mov_b32_e32 v24, v172
	v_mov_b32_e32 v25, v173
	v_mov_b32_e32 v26, v174
	v_mov_b32_e32 v27, v175
	v_mov_b32_e32 v28, v176
	v_mov_b32_e32 v29, v177
	v_mov_b32_e32 v30, v178
	v_mov_b32_e32 v31, v179
	v_pk_add_f32 v[16:17], v[16:17], v[24:25]
	v_pk_add_f32 v[22:23], v[22:23], v[30:31]
	v_pk_add_f32 v[20:21], v[20:21], v[28:29]
	v_pk_add_f32 v[18:19], v[18:19], v[26:27]
	global_store_dwordx4 v[44:45], v[20:23], off offset:512
	global_store_dwordx4 v[44:45], v[16:19], off offset:528
	v_cvt_pk_bf16_f32 v24, v20, v21
	v_cvt_pk_bf16_f32 v26, v16, v17
	v_cvt_pk_bf16_f32 v25, v22, v23
	v_cvt_pk_bf16_f32 v27, v18, v19
	s_nop 0
	v_mul_f32_e32 v21, v21, v21
	v_mul_f32_e32 v17, v17, v17
	v_fmac_f32_e32 v21, v20, v20
	v_fmac_f32_e32 v17, v16, v16
	v_fmac_f32_e32 v21, v22, v22
	v_fmac_f32_e32 v17, v18, v18
	v_fmac_f32_e32 v21, v23, v23
	v_fmac_f32_e32 v17, v19, v19
	v_add_f32_e32 v16, v21, v17
	v_add_f32_e32 v16, v36, v16
	ds_swizzle_b32 v17, v16 offset:swizzle(SWAP,16)
	global_store_dwordx4 v[40:41], v[24:27], off offset:256
	s_waitcnt lgkmcnt(0)
	v_add_f32_e32 v16, v16, v17
	ds_bpermute_b32 v17, v156, v16
	s_and_saveexec_b64 s[20:21], s[0:1]
	s_cbranch_execz .LBB0_2229
	v_lshlrev_b64 v[18:19], 6, v[34:35]
	v_lshl_add_u64 v[18:19], s[56:57], 0, v[18:19]
	v_lshl_add_u64 v[18:19], s[18:19], 2, v[18:19]
	s_lshl_b32 s22, s31, 2
	s_mov_b32 s23, s93
	v_lshl_add_u64 v[18:19], v[18:19], 0, s[22:23]
	s_waitcnt lgkmcnt(0)
	v_add_f32_e32 v16, v16, v17
	global_store_dword v[18:19], v16, off
.LBB0_2229:
	s_or_b64 exec, exec, s[20:21]
	v_or_b32_e32 v16, 48, v66
	s_waitcnt lgkmcnt(0)
	v_ashrrev_i32_e32 v17, 31, v16
	v_readlane_b32 s20, v252, 40
	v_lshlrev_b64 v[18:19], 12, v[16:17]
	v_readlane_b32 s21, v252, 41
	v_readlane_b32 s22, v252, 42
	v_readlane_b32 s23, v252, 43
	v_lshl_add_u64 v[18:19], s[20:21], 0, v[18:19]
	v_lshl_add_u64 v[26:27], v[146:147], 2, v[18:19]
	s_waitcnt vmcnt(11)
	v_mov_b32_e32 v18, v180
	v_mov_b32_e32 v19, v181
	v_mov_b32_e32 v20, v182
	v_mov_b32_e32 v21, v183
	v_mov_b32_e32 v22, v184
	v_mov_b32_e32 v23, v185
	v_mov_b32_e32 v24, v186
	v_mov_b32_e32 v25, v187
	v_readlane_b32 s20, v254, 6
	v_readlane_b32 s21, v254, 7
	v_pk_add_f32 v[8:9], v[8:9], v[18:19]
	v_pk_add_f32 v[14:15], v[14:15], v[24:25]
	v_pk_add_f32 v[12:13], v[12:13], v[22:23]
	v_pk_add_f32 v[10:11], v[10:11], v[20:21]
	global_store_dwordx4 v[26:27], v[12:15], off
	global_store_dwordx4 v[26:27], v[8:11], off offset:16
	v_cvt_pk_bf16_f32 v18, v12, v13
	v_cvt_pk_bf16_f32 v20, v8, v9
	v_lshlrev_b64 v[22:23], 11, v[16:17]
	v_mul_f32_e32 v13, v13, v13
	v_mul_f32_e32 v9, v9, v9
	v_lshl_add_u64 v[22:23], s[20:21], 0, v[22:23]
	v_fmac_f32_e32 v13, v12, v12
	v_fmac_f32_e32 v9, v8, v8
	v_lshl_add_u64 v[22:23], v[146:147], 1, v[22:23]
	v_fmac_f32_e32 v13, v14, v14
	v_fmac_f32_e32 v9, v10, v10
	v_cvt_pk_bf16_f32 v19, v14, v15
	v_cvt_pk_bf16_f32 v21, v10, v11
	global_store_dwordx4 v[22:23], v[18:21], off
	v_fmac_f32_e32 v13, v15, v15
	v_fmac_f32_e32 v9, v11, v11
	v_add_f32_e32 v18, v13, v9
	s_nop 1
	v_mov_b32_e32 v8, v188
	v_mov_b32_e32 v9, v189
	v_mov_b32_e32 v10, v190
	v_mov_b32_e32 v11, v191
	v_mov_b32_e32 v12, v192
	v_mov_b32_e32 v13, v193
	v_mov_b32_e32 v14, v194
	v_mov_b32_e32 v15, v195
	v_pk_add_f32 v[0:1], v[0:1], v[8:9]
	v_pk_add_f32 v[6:7], v[6:7], v[14:15]
	v_pk_add_f32 v[4:5], v[4:5], v[12:13]
	v_pk_add_f32 v[2:3], v[2:3], v[10:11]
	global_store_dwordx4 v[26:27], v[4:7], off offset:512
	global_store_dwordx4 v[26:27], v[0:3], off offset:528
	v_cvt_pk_bf16_f32 v8, v4, v5
	v_cvt_pk_bf16_f32 v10, v0, v1
	v_cvt_pk_bf16_f32 v9, v6, v7
	v_cvt_pk_bf16_f32 v11, v2, v3
	s_nop 0
	v_mul_f32_e32 v5, v5, v5
	v_mul_f32_e32 v1, v1, v1
	v_fmac_f32_e32 v5, v4, v4
	v_fmac_f32_e32 v1, v0, v0
	v_fmac_f32_e32 v5, v6, v6
	v_fmac_f32_e32 v1, v2, v2
	v_fmac_f32_e32 v5, v7, v7
	v_fmac_f32_e32 v1, v3, v3
	v_add_f32_e32 v0, v5, v1
	v_add_f32_e32 v0, v18, v0
	ds_swizzle_b32 v1, v0 offset:swizzle(SWAP,16)
	global_store_dwordx4 v[22:23], v[8:11], off offset:256
	s_waitcnt lgkmcnt(0)
	v_add_f32_e32 v0, v0, v1
	ds_bpermute_b32 v1, v156, v0
	s_and_saveexec_b64 s[20:21], s[0:1]
	s_cbranch_execz .LBB0_2231
	v_lshlrev_b64 v[2:3], 6, v[16:17]
	v_lshl_add_u64 v[2:3], s[56:57], 0, v[2:3]
	v_lshl_add_u64 v[2:3], s[18:19], 2, v[2:3]
	s_lshl_b32 s18, s31, 2
	s_mov_b32 s19, s93
	v_lshl_add_u64 v[2:3], v[2:3], 0, s[18:19]
	s_waitcnt lgkmcnt(0)
	v_add_f32_e32 v0, v0, v1
	global_store_dword v[2:3], v0, off
